# P1 projection epilogue rope branches: the sixteen output stores of a unit deferred to the end of the branch (results parked in consumed accumulators); on top of v138
# baseline (speedup 1.0000x reference)
; #define EPI_FENCE() asm volatile("" ::: "memory")
; __device__ __forceinline__ u32x4 pack8(f32x4 a, f32x4 b) { u32x4 w; w.x = cvt_pk_bf16(a[0], a[1]); w.y = cvt_pk_bf16(a[2], a[3]); w.z = cvt_pk_bf16(b[0], b[1]); w.w = cvt_pk_bf16(b[2], b[3]); return w; }
;   __device__ __forceinline__ void operator()(const AccT& acc, const pg8::Unit& u, int wr, int wc, int fr, int fq) const {
;     ...
;       bf16_t* dst = pn < 8 ? dq : dk; const int head = (pn - 4) & 3, sub = wc >> 1, i0 = 32 * (wc & 1) + 8 * fq;
; #pragma unroll
;       for (int ai = 0; ai < 2; ++ai)
; #pragma unroll
;         for (int m = 0; m < 4; ++m) { const int row = row0 + ai * 128 + m * 16;
;           f32x4 lo[2], hi[2];
; #pragma unroll
;           for (int n = 0; n < 2; ++n) { const f32x4 c = *(const f32x4*)(cos_d + (size_t)row * 64 + i0 + 4 * n), s = *(const f32x4*)(sin_d + (size_t)row * 64 + i0 + 4 * n);
;             const f32x4 a = acc[ai][0][m][n], b = acc[ai][1][m][n]; lo[n] = a * c - b * s; hi[n] = a * s + b * c; }
;           bf16_t* p = dst + (size_t)row * 1024 + head * 256 + sub * 128 + i0;
;           *(u32x4*)p = pack8(lo[0], lo[1]); *(u32x4*)(p + 64) = pack8(hi[0], hi[1]); if (m & 1) EPI_FENCE(); }
.LBB0_185:
	s_andn2_b64 vcc, exec, s[48:49]
	s_cbranch_vccnz .LBB0_187
	v_ashrrev_i32_e32 v179, 31, v178
	v_lshlrev_b64 v[128:129], 8, v[178:179]
	v_lshl_add_u64 v[130:131], v[160:161], 0, v[128:129]
	global_load_dwordx4 v[132:135], v[130:131], off
	global_load_dwordx4 v[136:139], v[130:131], off offset:16
	v_lshl_add_u64 v[128:129], v[158:159], 0, v[128:129]
	global_load_dwordx4 v[140:143], v[128:129], off
	global_load_dwordx4 v[188:191], v[128:129], off offset:16
	s_cmp_lt_u32 s97, 8
	s_mov_b32 s22, 0xcb00000
	s_cselect_b32 s22, s22, 0xeb00000
	s_add_u32 s22, s74, s22
	s_addc_u32 s43, s75, 0
	s_lshl_b32 s48, s97, 9
	s_and_b32 s48, s48, 0x600
	s_add_u32 s22, s22, s48
	s_addc_u32 s43, s43, 0
	s_add_u32 s48, s22, s94
	v_mov_b32_e32 v177, v155
	v_or_b32_e32 v130, 16, v178
	s_addc_u32 s49, s43, 0
	v_lshlrev_b64 v[180:181], 11, v[178:179]
	v_ashrrev_i32_e32 v131, 31, v130
	v_lshl_add_u64 v[128:129], s[48:49], 0, v[176:177]
	v_lshlrev_b64 v[194:195], 8, v[130:131]
	v_lshl_add_u64 v[180:181], v[128:129], 0, v[180:181]
	v_lshl_add_u64 v[196:197], v[160:161], 0, v[194:195]
	v_lshlrev_b64 v[130:131], 11, v[130:131]
	v_lshl_add_u64 v[130:131], v[128:129], 0, v[130:131]
	s_waitcnt vmcnt(0)
	v_pk_mul_f32 v[198:199], v[118:119], v[134:135]
	v_pk_mul_f32 v[134:135], v[122:123], v[134:135]
	v_pk_mul_f32 v[204:205], v[112:113], v[136:137]
	v_pk_mul_f32 v[200:201], v[116:117], v[132:133]
	v_pk_mul_f32 v[132:133], v[120:121], v[132:133]
	v_pk_mul_f32 v[202:203], v[114:115], v[138:139]
	v_pk_fma_f32 v[198:199], v[122:123], v[142:143], v[198:199] neg_lo:[0,0,1] neg_hi:[0,0,1]
	v_pk_fma_f32 v[142:143], v[118:119], v[142:143], v[134:135]
	v_pk_fma_f32 v[134:135], v[124:125], v[188:189], v[204:205] neg_lo:[0,0,1] neg_hi:[0,0,1]
	v_pk_mul_f32 v[138:139], v[126:127], v[138:139]
	v_pk_mul_f32 v[136:137], v[124:125], v[136:137]
	v_pk_fma_f32 v[200:201], v[120:121], v[140:141], v[200:201] neg_lo:[0,0,1] neg_hi:[0,0,1]
	v_pk_fma_f32 v[140:141], v[116:117], v[140:141], v[132:133]
	v_pk_fma_f32 v[202:203], v[126:127], v[190:191], v[202:203] neg_lo:[0,0,1] neg_hi:[0,0,1]
	v_cvt_pk_bf16_f32 v124, v200, v201
	v_cvt_pk_bf16_f32 v125, v198, v199
	v_cvt_pk_bf16_f32 v126, v134, v135
	v_pk_fma_f32 v[138:139], v[114:115], v[190:191], v[138:139]
	v_cvt_pk_bf16_f32 v127, v202, v203
	v_pk_fma_f32 v[136:137], v[112:113], v[188:189], v[136:137]
	v_mov_b64_e32 v[122:123], v[180:181]
	s_nop 1
	v_cvt_pk_bf16_f32 v116, v140, v141
	v_cvt_pk_bf16_f32 v117, v142, v143
	v_cvt_pk_bf16_f32 v118, v136, v137
	v_cvt_pk_bf16_f32 v119, v138, v139
	v_mov_b64_e32 v[120:121], v[180:181]
	global_load_dwordx4 v[134:137], v[196:197], off
	s_nop 0
	global_load_dwordx4 v[138:141], v[196:197], off offset:16
	v_lshl_add_u64 v[132:133], v[158:159], 0, v[194:195]
	global_load_dwordx4 v[188:191], v[132:133], off
	global_load_dwordx4 v[194:197], v[132:133], off offset:16
	v_or_b32_e32 v132, 32, v178
	v_ashrrev_i32_e32 v133, 31, v132
	v_lshlrev_b64 v[142:143], 8, v[132:133]
	v_lshl_add_u64 v[180:181], v[160:161], 0, v[142:143]
	v_lshlrev_b64 v[132:133], 11, v[132:133]
	s_waitcnt vmcnt(0)
	v_pk_mul_f32 v[198:199], v[102:103], v[136:137]
	v_pk_mul_f32 v[136:137], v[110:111], v[136:137]
	v_pk_mul_f32 v[204:205], v[96:97], v[138:139]
	v_pk_mul_f32 v[200:201], v[100:101], v[134:135]
	v_pk_mul_f32 v[134:135], v[108:109], v[134:135]
	v_pk_mul_f32 v[202:203], v[98:99], v[140:141]
	v_pk_fma_f32 v[198:199], v[110:111], v[190:191], v[198:199] neg_lo:[0,0,1] neg_hi:[0,0,1]
	v_pk_fma_f32 v[190:191], v[102:103], v[190:191], v[136:137]
	v_pk_fma_f32 v[136:137], v[104:105], v[194:195], v[204:205] neg_lo:[0,0,1] neg_hi:[0,0,1]
	v_pk_mul_f32 v[140:141], v[106:107], v[140:141]
	v_pk_mul_f32 v[138:139], v[104:105], v[138:139]
	v_pk_fma_f32 v[200:201], v[108:109], v[188:189], v[200:201] neg_lo:[0,0,1] neg_hi:[0,0,1]
	v_pk_fma_f32 v[188:189], v[100:101], v[188:189], v[134:135]
	v_pk_fma_f32 v[202:203], v[106:107], v[196:197], v[202:203] neg_lo:[0,0,1] neg_hi:[0,0,1]
	v_cvt_pk_bf16_f32 v112, v200, v201
	v_cvt_pk_bf16_f32 v113, v198, v199
	v_cvt_pk_bf16_f32 v114, v136, v137
	v_pk_fma_f32 v[140:141], v[98:99], v[196:197], v[140:141]
	v_cvt_pk_bf16_f32 v115, v202, v203
	v_pk_fma_f32 v[138:139], v[96:97], v[194:195], v[138:139]
	v_mov_b64_e32 v[110:111], v[130:131]
	v_lshl_add_u64 v[198:199], v[128:129], 0, v[132:133]
	s_nop 0
	v_cvt_pk_bf16_f32 v104, v188, v189
	v_cvt_pk_bf16_f32 v105, v190, v191
	v_cvt_pk_bf16_f32 v106, v138, v139
	v_cvt_pk_bf16_f32 v107, v140, v141
	v_mov_b64_e32 v[108:109], v[130:131]
	global_load_dwordx4 v[134:137], v[180:181], off
	global_load_dwordx4 v[138:141], v[180:181], off offset:16
	v_lshl_add_u64 v[130:131], v[158:159], 0, v[142:143]
	global_load_dwordx4 v[188:191], v[130:131], off
	global_load_dwordx4 v[194:197], v[130:131], off offset:16
	v_or_b32_e32 v130, 48, v178
	v_ashrrev_i32_e32 v131, 31, v130
	v_lshlrev_b64 v[142:143], 8, v[130:131]
	v_lshl_add_u64 v[180:181], v[160:161], 0, v[142:143]
	v_lshlrev_b64 v[130:131], 11, v[130:131]
	v_lshl_add_u64 v[130:131], v[128:129], 0, v[130:131]
	s_waitcnt vmcnt(0)
; #define EPI_FENCE() asm volatile("" ::: "memory")
; __device__ __forceinline__ u32x4 pack8(f32x4 a, f32x4 b) { u32x4 w; w.x = cvt_pk_bf16(a[0], a[1]); w.y = cvt_pk_bf16(a[2], a[3]); w.z = cvt_pk_bf16(b[0], b[1]); w.w = cvt_pk_bf16(b[2], b[3]); return w; }
;   __device__ __forceinline__ void operator()(const AccT& acc, const pg8::Unit& u, int wr, int wc, int fr, int fq) const {
;     ...
;       bf16_t* dst = pn < 8 ? dq : dk; const int head = (pn - 4) & 3, sub = wc >> 1, i0 = 32 * (wc & 1) + 8 * fq;
; #pragma unroll
;       for (int ai = 0; ai < 2; ++ai)
; #pragma unroll
;         for (int m = 0; m < 4; ++m) { const int row = row0 + ai * 128 + m * 16;
;           f32x4 lo[2], hi[2];
; #pragma unroll
;           for (int n = 0; n < 2; ++n) { const f32x4 c = *(const f32x4*)(cos_d + (size_t)row * 64 + i0 + 4 * n), s = *(const f32x4*)(sin_d + (size_t)row * 64 + i0 + 4 * n);
;             const f32x4 a = acc[ai][0][m][n], b = acc[ai][1][m][n]; lo[n] = a * c - b * s; hi[n] = a * s + b * c; }
;           bf16_t* p = dst + (size_t)row * 1024 + head * 256 + sub * 128 + i0;
;           *(u32x4*)p = pack8(lo[0], lo[1]); *(u32x4*)(p + 64) = pack8(hi[0], hi[1]); if (m & 1) EPI_FENCE(); }
	v_pk_mul_f32 v[132:133], v[86:87], v[136:137]
	v_pk_mul_f32 v[200:201], v[84:85], v[134:135]
	v_pk_mul_f32 v[134:135], v[92:93], v[134:135]
	v_pk_mul_f32 v[204:205], v[80:81], v[138:139]
	v_pk_mul_f32 v[136:137], v[94:95], v[136:137]
	v_pk_mul_f32 v[202:203], v[82:83], v[140:141]
	v_pk_fma_f32 v[206:207], v[94:95], v[190:191], v[132:133] neg_lo:[0,0,1] neg_hi:[0,0,1]
	v_pk_fma_f32 v[132:133], v[92:93], v[188:189], v[200:201] neg_lo:[0,0,1] neg_hi:[0,0,1]
	v_pk_fma_f32 v[188:189], v[84:85], v[188:189], v[134:135]
	v_pk_fma_f32 v[134:135], v[88:89], v[194:195], v[204:205] neg_lo:[0,0,1] neg_hi:[0,0,1]
	v_pk_mul_f32 v[140:141], v[90:91], v[140:141]
	v_pk_mul_f32 v[138:139], v[88:89], v[138:139]
	v_pk_fma_f32 v[136:137], v[86:87], v[190:191], v[136:137]
	v_pk_fma_f32 v[190:191], v[90:91], v[196:197], v[202:203] neg_lo:[0,0,1] neg_hi:[0,0,1]
	v_cvt_pk_bf16_f32 v100, v132, v133
	v_cvt_pk_bf16_f32 v101, v206, v207
	v_cvt_pk_bf16_f32 v102, v134, v135
	v_pk_fma_f32 v[140:141], v[82:83], v[196:197], v[140:141]
	v_cvt_pk_bf16_f32 v103, v190, v191
	v_pk_fma_f32 v[138:139], v[80:81], v[194:195], v[138:139]
	v_mov_b64_e32 v[98:99], v[198:199]
	s_nop 1
	v_cvt_pk_bf16_f32 v92, v188, v189
	v_cvt_pk_bf16_f32 v93, v136, v137
	v_cvt_pk_bf16_f32 v94, v138, v139
	v_cvt_pk_bf16_f32 v95, v140, v141
	v_mov_b64_e32 v[96:97], v[198:199]
	global_load_dwordx4 v[134:137], v[180:181], off
	s_nop 0
	global_load_dwordx4 v[138:141], v[180:181], off offset:16
	v_lshl_add_u64 v[132:133], v[158:159], 0, v[142:143]
	global_load_dwordx4 v[188:191], v[132:133], off
	global_load_dwordx4 v[194:197], v[132:133], off offset:16
	v_add_u32_e32 v132, 0x80, v178
	v_ashrrev_i32_e32 v133, 31, v132
	v_lshlrev_b64 v[142:143], 8, v[132:133]
	v_lshl_add_u64 v[180:181], v[160:161], 0, v[142:143]
	v_lshlrev_b64 v[132:133], 11, v[132:133]
	s_waitcnt vmcnt(0)
	v_pk_mul_f32 v[198:199], v[70:71], v[136:137]
	v_pk_mul_f32 v[136:137], v[78:79], v[136:137]
	v_pk_mul_f32 v[204:205], v[64:65], v[138:139]
	v_pk_mul_f32 v[200:201], v[68:69], v[134:135]
	v_pk_mul_f32 v[134:135], v[76:77], v[134:135]
	v_pk_mul_f32 v[202:203], v[66:67], v[140:141]
	v_pk_fma_f32 v[198:199], v[78:79], v[190:191], v[198:199] neg_lo:[0,0,1] neg_hi:[0,0,1]
	v_pk_fma_f32 v[190:191], v[70:71], v[190:191], v[136:137]
	v_pk_fma_f32 v[136:137], v[72:73], v[194:195], v[204:205] neg_lo:[0,0,1] neg_hi:[0,0,1]
	v_pk_mul_f32 v[140:141], v[74:75], v[140:141]
	v_pk_mul_f32 v[138:139], v[72:73], v[138:139]
	v_pk_fma_f32 v[200:201], v[76:77], v[188:189], v[200:201] neg_lo:[0,0,1] neg_hi:[0,0,1]
	v_pk_fma_f32 v[188:189], v[68:69], v[188:189], v[134:135]
	v_pk_fma_f32 v[202:203], v[74:75], v[196:197], v[202:203] neg_lo:[0,0,1] neg_hi:[0,0,1]
	v_cvt_pk_bf16_f32 v88, v200, v201
	v_cvt_pk_bf16_f32 v89, v198, v199
	v_cvt_pk_bf16_f32 v90, v136, v137
	v_pk_fma_f32 v[140:141], v[66:67], v[196:197], v[140:141]
	v_cvt_pk_bf16_f32 v91, v202, v203
	v_pk_fma_f32 v[138:139], v[64:65], v[194:195], v[138:139]
	v_mov_b64_e32 v[86:87], v[130:131]
	v_lshl_add_u64 v[198:199], v[128:129], 0, v[132:133]
	s_nop 0
	v_cvt_pk_bf16_f32 v80, v188, v189
	v_cvt_pk_bf16_f32 v81, v190, v191
	v_cvt_pk_bf16_f32 v82, v138, v139
	v_cvt_pk_bf16_f32 v83, v140, v141
	v_mov_b64_e32 v[84:85], v[130:131]
	global_load_dwordx4 v[134:137], v[180:181], off
	global_load_dwordx4 v[138:141], v[180:181], off offset:16
	v_lshl_add_u64 v[130:131], v[158:159], 0, v[142:143]
	global_load_dwordx4 v[188:191], v[130:131], off
	global_load_dwordx4 v[194:197], v[130:131], off offset:16
	v_add_u32_e32 v130, 0x90, v178
	v_ashrrev_i32_e32 v131, 31, v130
	v_lshlrev_b64 v[142:143], 8, v[130:131]
	v_lshl_add_u64 v[180:181], v[160:161], 0, v[142:143]
	v_lshlrev_b64 v[130:131], 11, v[130:131]
	v_lshl_add_u64 v[130:131], v[128:129], 0, v[130:131]
	s_waitcnt vmcnt(0)
	v_pk_mul_f32 v[132:133], v[54:55], v[136:137]
	v_pk_mul_f32 v[200:201], v[52:53], v[134:135]
	v_pk_mul_f32 v[134:135], v[60:61], v[134:135]
	v_pk_mul_f32 v[204:205], v[48:49], v[138:139]
	v_pk_mul_f32 v[136:137], v[62:63], v[136:137]
	v_pk_mul_f32 v[202:203], v[50:51], v[140:141]
	v_pk_fma_f32 v[206:207], v[62:63], v[190:191], v[132:133] neg_lo:[0,0,1] neg_hi:[0,0,1]
	v_pk_fma_f32 v[132:133], v[60:61], v[188:189], v[200:201] neg_lo:[0,0,1] neg_hi:[0,0,1]
	v_pk_fma_f32 v[188:189], v[52:53], v[188:189], v[134:135]
	v_pk_fma_f32 v[134:135], v[56:57], v[194:195], v[204:205] neg_lo:[0,0,1] neg_hi:[0,0,1]
	v_pk_mul_f32 v[140:141], v[58:59], v[140:141]
	v_pk_mul_f32 v[138:139], v[56:57], v[138:139]
	v_pk_fma_f32 v[136:137], v[54:55], v[190:191], v[136:137]
	v_pk_fma_f32 v[190:191], v[58:59], v[196:197], v[202:203] neg_lo:[0,0,1] neg_hi:[0,0,1]
	v_cvt_pk_bf16_f32 v76, v132, v133
	v_cvt_pk_bf16_f32 v77, v206, v207
	v_cvt_pk_bf16_f32 v78, v134, v135
	v_pk_fma_f32 v[140:141], v[50:51], v[196:197], v[140:141]
	v_cvt_pk_bf16_f32 v79, v190, v191
	v_pk_fma_f32 v[138:139], v[48:49], v[194:195], v[138:139]
	v_mov_b64_e32 v[74:75], v[198:199]
	s_nop 1
	v_cvt_pk_bf16_f32 v68, v188, v189
	v_cvt_pk_bf16_f32 v69, v136, v137
	v_cvt_pk_bf16_f32 v70, v138, v139
	v_cvt_pk_bf16_f32 v71, v140, v141
	v_mov_b64_e32 v[72:73], v[198:199]
	global_load_dwordx4 v[134:137], v[180:181], off
	s_nop 0
	global_load_dwordx4 v[138:141], v[180:181], off offset:16
	v_lshl_add_u64 v[132:133], v[158:159], 0, v[142:143]
	global_load_dwordx4 v[188:191], v[132:133], off
	global_load_dwordx4 v[194:197], v[132:133], off offset:16
	v_add_u32_e32 v132, 0xa0, v178
	v_ashrrev_i32_e32 v133, 31, v132
	v_lshlrev_b64 v[142:143], 8, v[132:133]
	v_lshl_add_u64 v[180:181], v[160:161], 0, v[142:143]
	s_waitcnt vmcnt(0)
; #define EPI_FENCE() asm volatile("" ::: "memory")
; __device__ __forceinline__ u32x4 pack8(f32x4 a, f32x4 b) { u32x4 w; w.x = cvt_pk_bf16(a[0], a[1]); w.y = cvt_pk_bf16(a[2], a[3]); w.z = cvt_pk_bf16(b[0], b[1]); w.w = cvt_pk_bf16(b[2], b[3]); return w; }
;   __device__ __forceinline__ void operator()(const AccT& acc, const pg8::Unit& u, int wr, int wc, int fr, int fq) const {
;     ...
;       bf16_t* dst = pn < 8 ? dq : dk; const int head = (pn - 4) & 3, sub = wc >> 1, i0 = 32 * (wc & 1) + 8 * fq;
; #pragma unroll
;       for (int ai = 0; ai < 2; ++ai)
; #pragma unroll
;         for (int m = 0; m < 4; ++m) { const int row = row0 + ai * 128 + m * 16;
;           f32x4 lo[2], hi[2];
; #pragma unroll
;           for (int n = 0; n < 2; ++n) { const f32x4 c = *(const f32x4*)(cos_d + (size_t)row * 64 + i0 + 4 * n), s = *(const f32x4*)(sin_d + (size_t)row * 64 + i0 + 4 * n);
;             const f32x4 a = acc[ai][0][m][n], b = acc[ai][1][m][n]; lo[n] = a * c - b * s; hi[n] = a * s + b * c; }
;           bf16_t* p = dst + (size_t)row * 1024 + head * 256 + sub * 128 + i0;
;           *(u32x4*)p = pack8(lo[0], lo[1]); *(u32x4*)(p + 64) = pack8(hi[0], hi[1]); if (m & 1) EPI_FENCE(); }
	v_pk_mul_f32 v[198:199], v[38:39], v[136:137]
	v_pk_mul_f32 v[136:137], v[46:47], v[136:137]
	v_pk_mul_f32 v[204:205], v[32:33], v[138:139]
	v_pk_mul_f32 v[200:201], v[36:37], v[134:135]
	v_pk_mul_f32 v[134:135], v[44:45], v[134:135]
	v_pk_mul_f32 v[202:203], v[34:35], v[140:141]
	v_pk_fma_f32 v[198:199], v[46:47], v[190:191], v[198:199] neg_lo:[0,0,1] neg_hi:[0,0,1]
	v_pk_fma_f32 v[190:191], v[38:39], v[190:191], v[136:137]
	v_pk_fma_f32 v[136:137], v[40:41], v[194:195], v[204:205] neg_lo:[0,0,1] neg_hi:[0,0,1]
	v_pk_mul_f32 v[140:141], v[42:43], v[140:141]
	v_pk_mul_f32 v[138:139], v[40:41], v[138:139]
	v_pk_fma_f32 v[200:201], v[44:45], v[188:189], v[200:201] neg_lo:[0,0,1] neg_hi:[0,0,1]
	v_pk_fma_f32 v[188:189], v[36:37], v[188:189], v[134:135]
	v_pk_fma_f32 v[202:203], v[42:43], v[196:197], v[202:203] neg_lo:[0,0,1] neg_hi:[0,0,1]
	v_cvt_pk_bf16_f32 v64, v200, v201
	v_cvt_pk_bf16_f32 v65, v198, v199
	v_cvt_pk_bf16_f32 v66, v136, v137
	v_pk_fma_f32 v[140:141], v[34:35], v[196:197], v[140:141]
	v_cvt_pk_bf16_f32 v67, v202, v203
	v_pk_fma_f32 v[138:139], v[32:33], v[194:195], v[138:139]
	v_mov_b64_e32 v[62:63], v[130:131]
	s_nop 1
	v_cvt_pk_bf16_f32 v56, v188, v189
	v_cvt_pk_bf16_f32 v57, v190, v191
	v_cvt_pk_bf16_f32 v58, v138, v139
	v_cvt_pk_bf16_f32 v59, v140, v141
	v_mov_b64_e32 v[60:61], v[130:131]
	global_load_dwordx4 v[134:137], v[180:181], off
	global_load_dwordx4 v[138:141], v[180:181], off offset:16
	v_lshl_add_u64 v[130:131], v[158:159], 0, v[142:143]
	global_load_dwordx4 v[188:191], v[130:131], off
	global_load_dwordx4 v[194:197], v[130:131], off offset:16
	v_lshlrev_b64 v[130:131], 11, v[132:133]
	v_add_u32_e32 v142, 0xb0, v178
	v_lshl_add_u64 v[200:201], v[128:129], 0, v[130:131]
	v_ashrrev_i32_e32 v143, 31, v142
	v_lshlrev_b64 v[180:181], 8, v[142:143]
	v_lshl_add_u64 v[198:199], v[160:161], 0, v[180:181]
	v_lshl_add_u64 v[180:181], v[158:159], 0, v[180:181]
	v_lshlrev_b64 v[142:143], 11, v[142:143]
	v_lshl_add_u64 v[142:143], v[128:129], 0, v[142:143]
	s_waitcnt vmcnt(0)
	v_pk_mul_f32 v[130:131], v[22:23], v[136:137]
	v_pk_mul_f32 v[132:133], v[20:21], v[134:135]
	v_pk_mul_f32 v[204:205], v[16:17], v[138:139]
	v_pk_mul_f32 v[134:135], v[28:29], v[134:135]
	v_pk_mul_f32 v[202:203], v[18:19], v[140:141]
	v_pk_fma_f32 v[206:207], v[30:31], v[190:191], v[130:131] neg_lo:[0,0,1] neg_hi:[0,0,1]
	v_pk_fma_f32 v[130:131], v[28:29], v[188:189], v[132:133] neg_lo:[0,0,1] neg_hi:[0,0,1]
	v_pk_fma_f32 v[132:133], v[24:25], v[194:195], v[204:205] neg_lo:[0,0,1] neg_hi:[0,0,1]
	v_pk_mul_f32 v[136:137], v[30:31], v[136:137]
	v_pk_mul_f32 v[140:141], v[26:27], v[140:141]
	v_pk_mul_f32 v[138:139], v[24:25], v[138:139]
	v_pk_fma_f32 v[134:135], v[20:21], v[188:189], v[134:135]
	v_pk_fma_f32 v[188:189], v[26:27], v[196:197], v[202:203] neg_lo:[0,0,1] neg_hi:[0,0,1]
	v_cvt_pk_bf16_f32 v52, v130, v131
	v_cvt_pk_bf16_f32 v53, v206, v207
	v_cvt_pk_bf16_f32 v54, v132, v133
	v_pk_fma_f32 v[136:137], v[22:23], v[190:191], v[136:137]
	v_cvt_pk_bf16_f32 v55, v188, v189
	v_pk_fma_f32 v[140:141], v[18:19], v[196:197], v[140:141]
	v_pk_fma_f32 v[138:139], v[16:17], v[194:195], v[138:139]
	v_mov_b64_e32 v[50:51], v[200:201]
	s_nop 1
	v_cvt_pk_bf16_f32 v44, v134, v135
	v_cvt_pk_bf16_f32 v45, v136, v137
	v_cvt_pk_bf16_f32 v46, v138, v139
	v_cvt_pk_bf16_f32 v47, v140, v141
	v_mov_b64_e32 v[48:49], v[200:201]
	global_load_dwordx4 v[130:133], v[198:199], off
	s_nop 0
	global_load_dwordx4 v[134:137], v[198:199], off offset:16
	global_load_dwordx4 v[138:141], v[180:181], off
	global_load_dwordx4 v[188:191], v[180:181], off offset:16
	s_waitcnt vmcnt(0)
	v_pk_mul_f32 v[128:129], v[6:7], v[132:133]
	v_pk_mul_f32 v[180:181], v[4:5], v[130:131]
	v_pk_mul_f32 v[130:131], v[12:13], v[130:131]
	v_pk_mul_f32 v[196:197], v[0:1], v[134:135]
	v_pk_mul_f32 v[132:133], v[14:15], v[132:133]
	v_pk_mul_f32 v[194:195], v[2:3], v[136:137]
	v_pk_fma_f32 v[198:199], v[14:15], v[140:141], v[128:129] neg_lo:[0,0,1] neg_hi:[0,0,1]
	v_pk_fma_f32 v[128:129], v[12:13], v[138:139], v[180:181] neg_lo:[0,0,1] neg_hi:[0,0,1]
	v_pk_fma_f32 v[138:139], v[4:5], v[138:139], v[130:131]
	v_pk_fma_f32 v[130:131], v[8:9], v[188:189], v[196:197] neg_lo:[0,0,1] neg_hi:[0,0,1]
	v_pk_mul_f32 v[136:137], v[10:11], v[136:137]
	v_pk_mul_f32 v[134:135], v[8:9], v[134:135]
	v_pk_fma_f32 v[132:133], v[6:7], v[140:141], v[132:133]
	v_pk_fma_f32 v[140:141], v[10:11], v[190:191], v[194:195] neg_lo:[0,0,1] neg_hi:[0,0,1]
	v_cvt_pk_bf16_f32 v40, v128, v129
	v_cvt_pk_bf16_f32 v41, v198, v199
	v_cvt_pk_bf16_f32 v42, v130, v131
	v_pk_fma_f32 v[136:137], v[2:3], v[190:191], v[136:137]
	v_cvt_pk_bf16_f32 v43, v140, v141
	v_pk_fma_f32 v[134:135], v[0:1], v[188:189], v[134:135]
	v_mov_b64_e32 v[38:39], v[142:143]
	s_nop 1
	v_cvt_pk_bf16_f32 v32, v138, v139
	v_cvt_pk_bf16_f32 v33, v132, v133
	v_cvt_pk_bf16_f32 v34, v134, v135
	v_cvt_pk_bf16_f32 v35, v136, v137
	v_mov_b64_e32 v[36:37], v[142:143]
	global_store_dwordx4 v[122:123], v[124:127], off
	global_store_dwordx4 v[120:121], v[116:119], off offset:128
	global_store_dwordx4 v[110:111], v[112:115], off
	global_store_dwordx4 v[108:109], v[104:107], off offset:128
	global_store_dwordx4 v[98:99], v[100:103], off
	global_store_dwordx4 v[96:97], v[92:95], off offset:128
	global_store_dwordx4 v[86:87], v[88:91], off
	global_store_dwordx4 v[84:85], v[80:83], off offset:128
	global_store_dwordx4 v[74:75], v[76:79], off
	global_store_dwordx4 v[72:73], v[68:71], off offset:128
	global_store_dwordx4 v[62:63], v[64:67], off
	global_store_dwordx4 v[60:61], v[56:59], off offset:128
	global_store_dwordx4 v[50:51], v[52:55], off
	global_store_dwordx4 v[48:49], v[44:47], off offset:128
	global_store_dwordx4 v[38:39], v[40:43], off
	global_store_dwordx4 v[36:37], v[32:35], off offset:128

; #define EPI_FENCE() asm volatile("" ::: "memory")
; __device__ __forceinline__ u32x4 pack8(f32x4 a, f32x4 b) { u32x4 w; w.x = cvt_pk_bf16(a[0], a[1]); w.y = cvt_pk_bf16(a[2], a[3]); w.z = cvt_pk_bf16(b[0], b[1]); w.w = cvt_pk_bf16(b[2], b[3]); return w; }
;   __device__ __forceinline__ void operator()(const AccT& acc, const pg8::Unit& u, int wr, int wc, int fr, int fq) const {
;     ...
;     } else if (pn == 3) {
;       if (wc == 0) {
; #pragma unroll
;         for (int ai = 0; ai < 2; ++ai)
; #pragma unroll
;           for (int m = 0; m < 4; ++m) { const int row = row0 + ai * 128 + m * 16;
;             f32x4 lo[2], hi[2];
; #pragma unroll
;             for (int n = 0; n < 2; ++n) { const f32x4 c = *(const f32x4*)(cos_r + (size_t)row * 32 + 8 * fq + 4 * n), s = *(const f32x4*)(sin_r + (size_t)row * 32 + 8 * fq + 4 * n);
;               const f32x4 a = acc[ai][0][m][n], b = acc[ai][1][m][n]; lo[n] = a * c - b * s; hi[n] = a * s + b * c; }
;             *(u32x4*)(kr + (size_t)row * 64 + 8 * fq) = pack8(lo[0], lo[1]);
;             *(u32x4*)(kr + (size_t)row * 64 + 32 + 8 * fq) = pack8(hi[0], hi[1]); if (m & 1) EPI_FENCE(); }
;       }
.LBB0_188:
	s_andn2_b64 vcc, exec, s[48:49]
	s_cbranch_vccnz .LBB0_191
	s_andn2_b64 vcc, exec, s[40:41]
	s_cbranch_vccnz .LBB0_191
	v_ashrrev_i32_e32 v179, 31, v178
	v_lshlrev_b64 v[132:133], 7, v[178:179]
	v_lshl_add_u64 v[134:135], v[164:165], 0, v[132:133]
	global_load_dwordx4 v[128:131], v[134:135], off
	global_load_dwordx4 v[140:143], v[134:135], off offset:16
	v_lshl_add_u64 v[134:135], v[162:163], 0, v[132:133]
	global_load_dwordx4 v[188:191], v[134:135], off
	global_load_dwordx4 v[194:197], v[134:135], off offset:16
	v_or_b32_e32 v136, 16, v178
	v_ashrrev_i32_e32 v137, 31, v136
	v_lshlrev_b64 v[138:139], 7, v[136:137]
	v_lshl_add_u64 v[134:135], v[166:167], 0, v[132:133]
	v_lshl_add_u64 v[136:137], v[164:165], 0, v[138:139]
	s_mov_b64 s[48:49], 0x4000
	s_mov_b64 s[44:45], 0x5000
	s_waitcnt vmcnt(0)
	v_pk_mul_f32 v[180:181], v[118:119], v[130:131]
	v_pk_mul_f32 v[130:131], v[122:123], v[130:131]
	v_pk_mul_f32 v[202:203], v[112:113], v[140:141]
	v_pk_mul_f32 v[198:199], v[116:117], v[128:129]
	v_pk_mul_f32 v[128:129], v[120:121], v[128:129]
	v_pk_mul_f32 v[200:201], v[114:115], v[142:143]
	v_pk_mul_f32 v[142:143], v[126:127], v[142:143]
	v_pk_mul_f32 v[140:141], v[124:125], v[140:141]
	v_pk_fma_f32 v[180:181], v[122:123], v[190:191], v[180:181] neg_lo:[0,0,1] neg_hi:[0,0,1]
	v_pk_fma_f32 v[190:191], v[118:119], v[190:191], v[130:131]
	v_pk_fma_f32 v[130:131], v[124:125], v[194:195], v[202:203] neg_lo:[0,0,1] neg_hi:[0,0,1]
	v_pk_fma_f32 v[198:199], v[120:121], v[188:189], v[198:199] neg_lo:[0,0,1] neg_hi:[0,0,1]
	v_pk_fma_f32 v[188:189], v[116:117], v[188:189], v[128:129]
	v_pk_fma_f32 v[200:201], v[126:127], v[196:197], v[200:201] neg_lo:[0,0,1] neg_hi:[0,0,1]
	v_pk_fma_f32 v[142:143], v[114:115], v[196:197], v[142:143]
	v_pk_fma_f32 v[140:141], v[112:113], v[194:195], v[140:141]
	v_cvt_pk_bf16_f32 v124, v198, v199
	v_cvt_pk_bf16_f32 v125, v180, v181
	v_cvt_pk_bf16_f32 v126, v130, v131
	v_cvt_pk_bf16_f32 v127, v200, v201
	v_mov_b64_e32 v[122:123], v[134:135]
	s_nop 1
	v_cvt_pk_bf16_f32 v116, v188, v189
	v_cvt_pk_bf16_f32 v117, v190, v191
	v_cvt_pk_bf16_f32 v118, v140, v141
	v_cvt_pk_bf16_f32 v119, v142, v143
	global_load_dwordx4 v[140:143], v[136:137], off
	global_load_dwordx4 v[188:191], v[136:137], off offset:16
	v_lshl_add_u64 v[136:137], v[162:163], 0, v[138:139]
	global_load_dwordx4 v[194:197], v[136:137], off
	global_load_dwordx4 v[198:201], v[136:137], off offset:16
	v_or_b32_e32 v136, 32, v178
	v_mov_b64_e32 v[120:121], v[134:135]
	v_ashrrev_i32_e32 v137, 31, v136
	v_lshl_add_u64 v[138:139], v[166:167], 0, v[138:139]
	v_lshlrev_b64 v[136:137], 7, v[136:137]
	v_lshl_add_u64 v[180:181], v[164:165], 0, v[136:137]
	s_waitcnt vmcnt(0)
	v_pk_mul_f32 v[128:129], v[102:103], v[142:143]
	v_pk_mul_f32 v[130:131], v[100:101], v[140:141]
	v_pk_mul_f32 v[202:203], v[96:97], v[188:189]
	v_pk_mul_f32 v[134:135], v[110:111], v[142:143]
	v_pk_mul_f32 v[142:143], v[98:99], v[190:191]
	v_pk_fma_f32 v[204:205], v[110:111], v[196:197], v[128:129] neg_lo:[0,0,1] neg_hi:[0,0,1]
	v_pk_fma_f32 v[128:129], v[108:109], v[194:195], v[130:131] neg_lo:[0,0,1] neg_hi:[0,0,1]
	v_pk_fma_f32 v[130:131], v[104:105], v[198:199], v[202:203] neg_lo:[0,0,1] neg_hi:[0,0,1]
	v_pk_mul_f32 v[140:141], v[108:109], v[140:141]
	v_pk_mul_f32 v[190:191], v[106:107], v[190:191]
	v_pk_mul_f32 v[188:189], v[104:105], v[188:189]
	v_pk_fma_f32 v[142:143], v[106:107], v[200:201], v[142:143] neg_lo:[0,0,1] neg_hi:[0,0,1]
	v_cvt_pk_bf16_f32 v112, v128, v129
	v_cvt_pk_bf16_f32 v113, v204, v205
	v_cvt_pk_bf16_f32 v114, v130, v131
	v_pk_fma_f32 v[134:135], v[102:103], v[196:197], v[134:135]
	v_cvt_pk_bf16_f32 v115, v142, v143
	v_pk_fma_f32 v[140:141], v[100:101], v[194:195], v[140:141]
	v_pk_fma_f32 v[190:191], v[98:99], v[200:201], v[190:191]
	v_pk_fma_f32 v[188:189], v[96:97], v[198:199], v[188:189]
	v_mov_b64_e32 v[110:111], v[138:139]
	s_nop 1
	v_cvt_pk_bf16_f32 v104, v140, v141
	v_cvt_pk_bf16_f32 v105, v134, v135
	v_cvt_pk_bf16_f32 v106, v188, v189
	v_cvt_pk_bf16_f32 v107, v190, v191
	v_mov_b64_e32 v[108:109], v[138:139]
	global_load_dwordx4 v[128:131], v[180:181], off
	global_load_dwordx4 v[140:143], v[180:181], off offset:16
	v_lshl_add_u64 v[134:135], v[162:163], 0, v[136:137]
	global_load_dwordx4 v[188:191], v[134:135], off
	global_load_dwordx4 v[194:197], v[134:135], off offset:16
	v_or_b32_e32 v134, 48, v178
	v_ashrrev_i32_e32 v135, 31, v134
	v_lshlrev_b64 v[138:139], 7, v[134:135]
	v_lshl_add_u64 v[134:135], v[166:167], 0, v[136:137]
	v_lshl_add_u64 v[136:137], v[164:165], 0, v[138:139]
	s_waitcnt vmcnt(0)
	v_pk_mul_f32 v[180:181], v[86:87], v[130:131]
	v_pk_mul_f32 v[130:131], v[94:95], v[130:131]
	v_pk_mul_f32 v[202:203], v[80:81], v[140:141]
	v_pk_mul_f32 v[198:199], v[84:85], v[128:129]
	v_pk_mul_f32 v[128:129], v[92:93], v[128:129]
	v_pk_mul_f32 v[200:201], v[82:83], v[142:143]
	v_pk_mul_f32 v[142:143], v[90:91], v[142:143]
	v_pk_mul_f32 v[140:141], v[88:89], v[140:141]
	v_pk_fma_f32 v[180:181], v[94:95], v[190:191], v[180:181] neg_lo:[0,0,1] neg_hi:[0,0,1]
	v_pk_fma_f32 v[190:191], v[86:87], v[190:191], v[130:131]
	v_pk_fma_f32 v[130:131], v[88:89], v[194:195], v[202:203] neg_lo:[0,0,1] neg_hi:[0,0,1]
	v_pk_fma_f32 v[198:199], v[92:93], v[188:189], v[198:199] neg_lo:[0,0,1] neg_hi:[0,0,1]
	v_pk_fma_f32 v[188:189], v[84:85], v[188:189], v[128:129]
	v_pk_fma_f32 v[200:201], v[90:91], v[196:197], v[200:201] neg_lo:[0,0,1] neg_hi:[0,0,1]
	v_pk_fma_f32 v[142:143], v[82:83], v[196:197], v[142:143]
	v_pk_fma_f32 v[140:141], v[80:81], v[194:195], v[140:141]
	v_cvt_pk_bf16_f32 v100, v198, v199
	v_cvt_pk_bf16_f32 v101, v180, v181
	v_cvt_pk_bf16_f32 v102, v130, v131
	v_cvt_pk_bf16_f32 v103, v200, v201
	v_mov_b64_e32 v[98:99], v[134:135]
	s_nop 1
	v_cvt_pk_bf16_f32 v92, v188, v189
	v_cvt_pk_bf16_f32 v93, v190, v191
	v_cvt_pk_bf16_f32 v94, v140, v141
	v_cvt_pk_bf16_f32 v95, v142, v143
	global_load_dwordx4 v[140:143], v[136:137], off
	global_load_dwordx4 v[188:191], v[136:137], off offset:16
	v_lshl_add_u64 v[136:137], v[162:163], 0, v[138:139]
	global_load_dwordx4 v[194:197], v[136:137], off
	global_load_dwordx4 v[198:201], v[136:137], off offset:16
	v_lshl_add_u64 v[138:139], v[166:167], 0, v[138:139]
	v_mov_b64_e32 v[96:97], v[134:135]
	v_lshl_add_u64 v[136:137], v[132:133], 0, s[48:49]
	v_lshl_add_u64 v[180:181], v[164:165], 0, v[136:137]
	s_mov_b64 s[48:49], 0x4800
	s_waitcnt vmcnt(0)
; #define EPI_FENCE() asm volatile("" ::: "memory")
; __device__ __forceinline__ u32x4 pack8(f32x4 a, f32x4 b) { u32x4 w; w.x = cvt_pk_bf16(a[0], a[1]); w.y = cvt_pk_bf16(a[2], a[3]); w.z = cvt_pk_bf16(b[0], b[1]); w.w = cvt_pk_bf16(b[2], b[3]); return w; }
;   __device__ __forceinline__ void operator()(const AccT& acc, const pg8::Unit& u, int wr, int wc, int fr, int fq) const {
;     ...
;     } else if (pn == 3) {
;       if (wc == 0) {
; #pragma unroll
;         for (int ai = 0; ai < 2; ++ai)
; #pragma unroll
;           for (int m = 0; m < 4; ++m) { const int row = row0 + ai * 128 + m * 16;
;             f32x4 lo[2], hi[2];
; #pragma unroll
;             for (int n = 0; n < 2; ++n) { const f32x4 c = *(const f32x4*)(cos_r + (size_t)row * 32 + 8 * fq + 4 * n), s = *(const f32x4*)(sin_r + (size_t)row * 32 + 8 * fq + 4 * n);
;               const f32x4 a = acc[ai][0][m][n], b = acc[ai][1][m][n]; lo[n] = a * c - b * s; hi[n] = a * s + b * c; }
;             *(u32x4*)(kr + (size_t)row * 64 + 8 * fq) = pack8(lo[0], lo[1]);
;             *(u32x4*)(kr + (size_t)row * 64 + 32 + 8 * fq) = pack8(hi[0], hi[1]); if (m & 1) EPI_FENCE(); }
;       }
	v_pk_mul_f32 v[128:129], v[70:71], v[142:143]
	v_pk_mul_f32 v[130:131], v[68:69], v[140:141]
	v_pk_mul_f32 v[202:203], v[64:65], v[188:189]
	v_pk_mul_f32 v[134:135], v[78:79], v[142:143]
	v_pk_mul_f32 v[142:143], v[66:67], v[190:191]
	v_pk_fma_f32 v[204:205], v[78:79], v[196:197], v[128:129] neg_lo:[0,0,1] neg_hi:[0,0,1]
	v_pk_fma_f32 v[128:129], v[76:77], v[194:195], v[130:131] neg_lo:[0,0,1] neg_hi:[0,0,1]
	v_pk_fma_f32 v[130:131], v[72:73], v[198:199], v[202:203] neg_lo:[0,0,1] neg_hi:[0,0,1]
	v_pk_mul_f32 v[140:141], v[76:77], v[140:141]
	v_pk_mul_f32 v[190:191], v[74:75], v[190:191]
	v_pk_mul_f32 v[188:189], v[72:73], v[188:189]
	v_pk_fma_f32 v[142:143], v[74:75], v[200:201], v[142:143] neg_lo:[0,0,1] neg_hi:[0,0,1]
	v_cvt_pk_bf16_f32 v88, v128, v129
	v_cvt_pk_bf16_f32 v89, v204, v205
	v_cvt_pk_bf16_f32 v90, v130, v131
	v_pk_fma_f32 v[134:135], v[70:71], v[196:197], v[134:135]
	v_cvt_pk_bf16_f32 v91, v142, v143
	v_pk_fma_f32 v[140:141], v[68:69], v[194:195], v[140:141]
	v_pk_fma_f32 v[190:191], v[66:67], v[200:201], v[190:191]
	v_pk_fma_f32 v[188:189], v[64:65], v[198:199], v[188:189]
	v_mov_b64_e32 v[86:87], v[138:139]
	s_nop 1
	v_cvt_pk_bf16_f32 v80, v140, v141
	v_cvt_pk_bf16_f32 v81, v134, v135
	v_cvt_pk_bf16_f32 v82, v188, v189
	v_cvt_pk_bf16_f32 v83, v190, v191
	v_mov_b64_e32 v[84:85], v[138:139]
	global_load_dwordx4 v[128:131], v[180:181], off
	global_load_dwordx4 v[140:143], v[180:181], off offset:16
	v_lshl_add_u64 v[134:135], v[162:163], 0, v[136:137]
	global_load_dwordx4 v[188:191], v[134:135], off
	global_load_dwordx4 v[194:197], v[134:135], off offset:16
	v_lshl_add_u64 v[138:139], v[132:133], 0, s[48:49]
	v_lshl_add_u64 v[134:135], v[166:167], 0, v[136:137]
	v_lshl_add_u64 v[136:137], v[164:165], 0, v[138:139]
	s_waitcnt vmcnt(0)
	v_pk_mul_f32 v[180:181], v[54:55], v[130:131]
	v_pk_mul_f32 v[130:131], v[62:63], v[130:131]
	v_pk_mul_f32 v[202:203], v[48:49], v[140:141]
	v_pk_mul_f32 v[198:199], v[52:53], v[128:129]
	v_pk_mul_f32 v[128:129], v[60:61], v[128:129]
	v_pk_mul_f32 v[200:201], v[50:51], v[142:143]
	v_pk_mul_f32 v[142:143], v[58:59], v[142:143]
	v_pk_mul_f32 v[140:141], v[56:57], v[140:141]
	v_pk_fma_f32 v[180:181], v[62:63], v[190:191], v[180:181] neg_lo:[0,0,1] neg_hi:[0,0,1]
	v_pk_fma_f32 v[190:191], v[54:55], v[190:191], v[130:131]
	v_pk_fma_f32 v[130:131], v[56:57], v[194:195], v[202:203] neg_lo:[0,0,1] neg_hi:[0,0,1]
	v_pk_fma_f32 v[198:199], v[60:61], v[188:189], v[198:199] neg_lo:[0,0,1] neg_hi:[0,0,1]
	v_pk_fma_f32 v[188:189], v[52:53], v[188:189], v[128:129]
	v_pk_fma_f32 v[200:201], v[58:59], v[196:197], v[200:201] neg_lo:[0,0,1] neg_hi:[0,0,1]
	v_pk_fma_f32 v[142:143], v[50:51], v[196:197], v[142:143]
	v_pk_fma_f32 v[140:141], v[48:49], v[194:195], v[140:141]
	v_cvt_pk_bf16_f32 v76, v198, v199
	v_cvt_pk_bf16_f32 v77, v180, v181
	v_cvt_pk_bf16_f32 v78, v130, v131
	v_cvt_pk_bf16_f32 v79, v200, v201
	v_mov_b64_e32 v[74:75], v[134:135]
	s_nop 1
	v_cvt_pk_bf16_f32 v68, v188, v189
	v_cvt_pk_bf16_f32 v69, v190, v191
	v_cvt_pk_bf16_f32 v70, v140, v141
	v_cvt_pk_bf16_f32 v71, v142, v143
	global_load_dwordx4 v[140:143], v[136:137], off
	global_load_dwordx4 v[188:191], v[136:137], off offset:16
	v_lshl_add_u64 v[136:137], v[162:163], 0, v[138:139]
	global_load_dwordx4 v[194:197], v[136:137], off
	global_load_dwordx4 v[198:201], v[136:137], off offset:16
	v_lshl_add_u64 v[138:139], v[166:167], 0, v[138:139]
	v_mov_b64_e32 v[72:73], v[134:135]
	v_lshl_add_u64 v[136:137], v[132:133], 0, s[44:45]
	v_lshl_add_u64 v[180:181], v[164:165], 0, v[136:137]
	s_mov_b64 s[44:45], 0x5800
	s_waitcnt vmcnt(0)
	v_pk_mul_f32 v[128:129], v[38:39], v[142:143]
	v_pk_mul_f32 v[130:131], v[36:37], v[140:141]
	v_pk_mul_f32 v[202:203], v[32:33], v[188:189]
	v_pk_mul_f32 v[134:135], v[46:47], v[142:143]
	v_pk_mul_f32 v[142:143], v[34:35], v[190:191]
	v_pk_fma_f32 v[204:205], v[46:47], v[196:197], v[128:129] neg_lo:[0,0,1] neg_hi:[0,0,1]
	v_pk_fma_f32 v[128:129], v[44:45], v[194:195], v[130:131] neg_lo:[0,0,1] neg_hi:[0,0,1]
	v_pk_fma_f32 v[130:131], v[40:41], v[198:199], v[202:203] neg_lo:[0,0,1] neg_hi:[0,0,1]
	v_pk_mul_f32 v[140:141], v[44:45], v[140:141]
	v_pk_mul_f32 v[190:191], v[42:43], v[190:191]
	v_pk_mul_f32 v[188:189], v[40:41], v[188:189]
	v_pk_fma_f32 v[142:143], v[42:43], v[200:201], v[142:143] neg_lo:[0,0,1] neg_hi:[0,0,1]
	v_cvt_pk_bf16_f32 v64, v128, v129
	v_cvt_pk_bf16_f32 v65, v204, v205
	v_cvt_pk_bf16_f32 v66, v130, v131
	v_pk_fma_f32 v[134:135], v[38:39], v[196:197], v[134:135]
	v_cvt_pk_bf16_f32 v67, v142, v143
	v_pk_fma_f32 v[140:141], v[36:37], v[194:195], v[140:141]
	v_pk_fma_f32 v[190:191], v[34:35], v[200:201], v[190:191]
	v_pk_fma_f32 v[188:189], v[32:33], v[198:199], v[188:189]
	v_mov_b64_e32 v[62:63], v[138:139]
	s_nop 1
	v_cvt_pk_bf16_f32 v56, v140, v141
	v_cvt_pk_bf16_f32 v57, v134, v135
	v_cvt_pk_bf16_f32 v58, v188, v189
	v_cvt_pk_bf16_f32 v59, v190, v191
	v_mov_b64_e32 v[60:61], v[138:139]
	global_load_dwordx4 v[138:141], v[180:181], off
	global_load_dwordx4 v[188:191], v[180:181], off offset:16
	v_lshl_add_u64 v[128:129], v[162:163], 0, v[136:137]
	global_load_dwordx4 v[194:197], v[128:129], off
	global_load_dwordx4 v[198:201], v[128:129], off offset:16
	v_lshl_add_u64 v[130:131], v[132:133], 0, s[44:45]
	v_lshl_add_u64 v[128:129], v[166:167], 0, v[136:137]
	v_lshl_add_u64 v[142:143], v[164:165], 0, v[130:131]
	s_waitcnt vmcnt(0)
; #define EPI_FENCE() asm volatile("" ::: "memory")
; __device__ __forceinline__ u32x4 pack8(f32x4 a, f32x4 b) { u32x4 w; w.x = cvt_pk_bf16(a[0], a[1]); w.y = cvt_pk_bf16(a[2], a[3]); w.z = cvt_pk_bf16(b[0], b[1]); w.w = cvt_pk_bf16(b[2], b[3]); return w; }
;   __device__ __forceinline__ void operator()(const AccT& acc, const pg8::Unit& u, int wr, int wc, int fr, int fq) const {
;     ...
;     } else if (pn == 3) {
;       if (wc == 0) {
; #pragma unroll
;         for (int ai = 0; ai < 2; ++ai)
; #pragma unroll
;           for (int m = 0; m < 4; ++m) { const int row = row0 + ai * 128 + m * 16;
;             f32x4 lo[2], hi[2];
; #pragma unroll
;             for (int n = 0; n < 2; ++n) { const f32x4 c = *(const f32x4*)(cos_r + (size_t)row * 32 + 8 * fq + 4 * n), s = *(const f32x4*)(sin_r + (size_t)row * 32 + 8 * fq + 4 * n);
;               const f32x4 a = acc[ai][0][m][n], b = acc[ai][1][m][n]; lo[n] = a * c - b * s; hi[n] = a * s + b * c; }
;             *(u32x4*)(kr + (size_t)row * 64 + 8 * fq) = pack8(lo[0], lo[1]);
;             *(u32x4*)(kr + (size_t)row * 64 + 32 + 8 * fq) = pack8(hi[0], hi[1]); if (m & 1) EPI_FENCE(); }
;       }
	v_pk_mul_f32 v[132:133], v[22:23], v[140:141]
	v_pk_mul_f32 v[134:135], v[20:21], v[138:139]
	v_pk_mul_f32 v[180:181], v[16:17], v[188:189]
	v_pk_mul_f32 v[136:137], v[30:31], v[140:141]
	v_pk_mul_f32 v[138:139], v[28:29], v[138:139]
	v_pk_mul_f32 v[140:141], v[18:19], v[190:191]
	v_pk_mul_f32 v[190:191], v[26:27], v[190:191]
	v_pk_fma_f32 v[202:203], v[30:31], v[196:197], v[132:133] neg_lo:[0,0,1] neg_hi:[0,0,1]
	v_pk_fma_f32 v[132:133], v[28:29], v[194:195], v[134:135] neg_lo:[0,0,1] neg_hi:[0,0,1]
	v_pk_fma_f32 v[134:135], v[24:25], v[198:199], v[180:181] neg_lo:[0,0,1] neg_hi:[0,0,1]
	v_pk_mul_f32 v[188:189], v[24:25], v[188:189]
	v_pk_fma_f32 v[136:137], v[22:23], v[196:197], v[136:137]
	v_pk_fma_f32 v[138:139], v[20:21], v[194:195], v[138:139]
	v_pk_fma_f32 v[140:141], v[26:27], v[200:201], v[140:141] neg_lo:[0,0,1] neg_hi:[0,0,1]
	v_pk_fma_f32 v[180:181], v[18:19], v[200:201], v[190:191]
	v_cvt_pk_bf16_f32 v52, v132, v133
	v_cvt_pk_bf16_f32 v53, v202, v203
	v_cvt_pk_bf16_f32 v54, v134, v135
	v_cvt_pk_bf16_f32 v55, v140, v141
	v_pk_fma_f32 v[188:189], v[16:17], v[198:199], v[188:189]
	v_mov_b64_e32 v[50:51], v[128:129]
	s_nop 1
	v_cvt_pk_bf16_f32 v44, v138, v139
	v_cvt_pk_bf16_f32 v45, v136, v137
	v_cvt_pk_bf16_f32 v46, v188, v189
	v_cvt_pk_bf16_f32 v47, v180, v181
	global_load_dwordx4 v[136:139], v[142:143], off
	s_nop 0
	global_load_dwordx4 v[140:143], v[142:143], off offset:16
	v_lshl_add_u64 v[180:181], v[162:163], 0, v[130:131]
	global_load_dwordx4 v[188:191], v[180:181], off
	global_load_dwordx4 v[194:197], v[180:181], off offset:16
	v_lshl_add_u64 v[180:181], v[166:167], 0, v[130:131]
	v_mov_b64_e32 v[48:49], v[128:129]
	s_waitcnt vmcnt(0)
	v_pk_mul_f32 v[128:129], v[6:7], v[138:139]
	v_pk_mul_f32 v[130:131], v[4:5], v[136:137]
	v_pk_mul_f32 v[132:133], v[14:15], v[138:139]
	v_pk_mul_f32 v[138:139], v[0:1], v[140:141]
	v_pk_mul_f32 v[134:135], v[12:13], v[136:137]
	v_pk_mul_f32 v[136:137], v[2:3], v[142:143]
	v_pk_fma_f32 v[198:199], v[14:15], v[190:191], v[128:129] neg_lo:[0,0,1] neg_hi:[0,0,1]
	v_pk_fma_f32 v[128:129], v[12:13], v[188:189], v[130:131] neg_lo:[0,0,1] neg_hi:[0,0,1]
	v_pk_fma_f32 v[130:131], v[8:9], v[194:195], v[138:139] neg_lo:[0,0,1] neg_hi:[0,0,1]
	v_pk_mul_f32 v[142:143], v[10:11], v[142:143]
	v_pk_mul_f32 v[140:141], v[8:9], v[140:141]
	v_pk_fma_f32 v[136:137], v[10:11], v[196:197], v[136:137] neg_lo:[0,0,1] neg_hi:[0,0,1]
	v_cvt_pk_bf16_f32 v40, v128, v129
	v_cvt_pk_bf16_f32 v41, v198, v199
	v_cvt_pk_bf16_f32 v42, v130, v131
	v_pk_fma_f32 v[132:133], v[6:7], v[190:191], v[132:133]
	v_cvt_pk_bf16_f32 v43, v136, v137
	v_pk_fma_f32 v[134:135], v[4:5], v[188:189], v[134:135]
	v_pk_fma_f32 v[138:139], v[2:3], v[196:197], v[142:143]
	v_pk_fma_f32 v[140:141], v[0:1], v[194:195], v[140:141]
	v_mov_b64_e32 v[38:39], v[180:181]
	s_nop 1
	v_cvt_pk_bf16_f32 v32, v134, v135
	v_cvt_pk_bf16_f32 v33, v132, v133
	v_cvt_pk_bf16_f32 v34, v140, v141
	v_cvt_pk_bf16_f32 v35, v138, v139
	v_mov_b64_e32 v[36:37], v[180:181]
	global_store_dwordx4 v[122:123], v[124:127], off
	global_store_dwordx4 v[120:121], v[116:119], off offset:64
	global_store_dwordx4 v[110:111], v[112:115], off
	global_store_dwordx4 v[108:109], v[104:107], off offset:64
	global_store_dwordx4 v[98:99], v[100:103], off
	global_store_dwordx4 v[96:97], v[92:95], off offset:64
	global_store_dwordx4 v[86:87], v[88:91], off
	global_store_dwordx4 v[84:85], v[80:83], off offset:64
	global_store_dwordx4 v[74:75], v[76:79], off
	global_store_dwordx4 v[72:73], v[68:71], off offset:64
	global_store_dwordx4 v[62:63], v[64:67], off
	global_store_dwordx4 v[60:61], v[56:59], off offset:64
	global_store_dwordx4 v[50:51], v[52:55], off
	global_store_dwordx4 v[48:49], v[44:47], off offset:64
	global_store_dwordx4 v[38:39], v[40:43], off
	global_store_dwordx4 v[36:37], v[32:35], off offset:64
